# swiglu GEMM phases: 7 of 8 packed output quads per tile held in spare VGPRs and stored one per K-loop wait point of the next tile instead of a burst between tiles
# speedup vs baseline: 1.0048x; 1.0048x over previous
; #define PG8_STAGE(bufoff, gbase, voff) do { _Pragma("unroll") for (int _i = 0; _i < 2; ++_i) \
;         __builtin_amdgcn_global_load_lds((const unsigned*)((const char*)(gbase) + (voff)[_i]), (PG8_LAS unsigned*)(lds + (bufoff) + ldsw + _i * 8192), 16, 0, 0); } while (0)
; #define PG8_WAIT_V(n) asm volatile("s_waitcnt vmcnt(" #n ")" ::: "memory")
; template <class Epi, class Sched>
; __device__ __forceinline__ void gemm_phase(PG8_LAS unsigned char* lds, const Gemm g, const Sched& S, const Epi& E) {
;     const int tid = threadIdx.x, wid = __builtin_amdgcn_readfirstlane(tid >> 6), lane = tid & 63, wr = wid >> 2, wc = wid & 3, fr = lane & 15, fq = lane >> 4;
;     const int K = g.K, nt = K / BK;
;     unsigned voffA[2], voffB[2];
; #pragma unroll
;     for (int i = 0; i < 2; ++i) { int R, C; stage_rc(tid * 16 + i * 8192, R, C); const int Rb = Epi::PERM ? ((R & ~31) + perm32(R & 31)) : R;
;         voffA[i] = (unsigned)(R * g.lda + C) * 2u; voffB[i] = (unsigned)(Rb * K + C) * 2u; }
;     const size_t kstep = (size_t)(BK * 2);
;     const size_t hstepA = (size_t)HALF * g.lda * 2, hstepB = (size_t)HALF * K * 2;
;     const size_t tstepA = 2 * hstepA, tstepB = 2 * hstepB;
;     const unsigned ldsw = (unsigned)wid * 1024u;
;     const int aoff = lds_byte(wr * 64 + fr, fq * 8), boff = lds_byte(wc * 32 + fr, fq * 8);
;     ...
;     Unit cur, nxt; int ui = 0;
;     if (!S.next(0, cur)) return;
;     f32x4 acc[2][2][4][2];
; #pragma unroll
;     for (int a = 0; a < 2; ++a)
; #pragma unroll
;         for (int b = 0; b < 2; ++b)
; #pragma unroll
;             for (int m = 0; m < 4; ++m)
; #pragma unroll
;                 for (int n = 0; n < 2; ++n) acc[a][b][m][n] = (f32x4){0.f, 0.f, 0.f, 0.f};
;     bf16x8 At[4][2], B0[2][2], B1[2][2];
;     const char* cA = (const char*)g.A + (size_t)cur.pm * tstepA + (g.agroup ? (size_t)(cur.pn / g.agroup) * K * 2 : (size_t)0); const char* cB = (const char*)g.Bt + (size_t)cur.pn * tstepB;
;     S.a_ready(cur);
;     PG8_STAGE(PG8_SB(0, 0), cB, voffB); PG8_STAGE(PG8_SA(0, 0), cA, voffA); PG8_STAGE(PG8_SB(0, 1), cB + hstepB, voffB); PG8_STAGE(PG8_SA(0, 1), cA + hstepA, voffA);
;     if (wr == 1) PG8_BAR;
;     PG8_WAIT_V(4); PG8_BAR;
;     PG8_STAGE(PG8_SB(1, 0), cB + kstep, voffB); PG8_STAGE(PG8_SA(1, 0), cA + kstep, voffA); PG8_STAGE(PG8_SB(1, 1), cB + hstepB + kstep, voffB);
;     PG8_WAIT_V(6); PG8_BAR;
.LBB0_474:
	s_cmp_lt_i32 s62, 6
	s_cselect_b64 s[6:7], -1, 0
	s_and_b64 s[8:9], s[6:7], s[8:9]
	s_andn2_b64 vcc, exec, s[8:9]
	s_cbranch_vccnz .LBB0_487
	s_mov_b64 s[98:99], 0
	s_cmpk_gt_i32 s2, 0xaff
	v_mov_b32_e32 v2, v1
	s_mov_b64 s[6:7], s[0:1]
	v_readfirstlane_b32 s3, v1
	s_cbranch_scc1 .LBB0_487
	v_lshrrev_b32_e32 v4, 1, v1
	v_and_b32_e32 v13, 24, v4
	v_lshrrev_b32_e32 v4, 5, v1
	v_and_b32_e32 v4, 4, v4
	v_bfe_u32 v5, v1, 2, 2
	v_lshlrev_b32_e32 v2, 4, v1
	v_and_b32_e32 v3, 32, v1
	v_bfe_u32 v12, v1, 2, 4
	v_or3_b32 v4, v4, v5, v13
	v_lshrrev_b32_e32 v5, 3, v1
	s_movk_i32 s10, 0x70
	v_bitop3_b32 v10, v2, v3, 48 bitop3:0x6c
	v_and_b32_e32 v11, 64, v1
	v_and_or_b32 v6, v5, s10, v12
	s_movk_i32 s10, 0x60
	v_add_u32_e32 v14, 0x2000, v2
	v_or_b32_e32 v3, v10, v11
	v_and_or_b32 v5, v5, s10, v4
	v_lshrrev_b32_e32 v2, 7, v14
	s_movk_i32 s10, 0xf0
	v_lshl_or_b32 v132, v5, 12, v3
	v_and_or_b32 v5, v2, s10, v12
	s_load_dwordx2 s[10:11], s[6:7], 0xc8
	s_movk_i32 s6, 0xe0
	v_and_or_b32 v2, v2, s6, v4
	s_movk_i32 s38, 0x161
	v_lshl_or_b32 v136, v2, 12, v3
	s_waitcnt lgkmcnt(0)
	s_add_u32 s30, s10, 0x10dcc000
	s_addc_u32 s31, s11, 0
	s_add_u32 s34, s10, 0x650c000
	s_addc_u32 s35, s11, 0
	s_ashr_i32 s37, s2, 31
	s_lshr_b32 s6, s37, 29
	s_add_i32 s6, s2, s6
	s_lshr_b32 s12, s3, 6
	s_ashr_i32 s13, s6, 3
	s_and_b32 s6, s6, -8
	s_lshr_b32 s7, s3, 8
	s_lshl_b32 s36, s12, 10
	s_sub_i32 s6, s2, s6
	s_cmp_lt_i32 s6, 0
	s_cselect_b32 s14, s38, 0x160
	s_mul_i32 s6, s6, s14
	s_add_i32 s6, s6, s13
	s_mul_hi_i32 s13, s6, 0x2e8ba2e9
	s_lshr_b32 s14, s13, 31
	s_ashr_i32 s13, s13, 5
	s_add_i32 s13, s13, s14
	s_lshl_b32 s14, s13, 2
	s_mulk_i32 s13, 0xb0
	s_sub_i32 s13, s6, s13
	s_sext_i32_i16 s6, s13
	s_bfe_u32 s6, s6, 0x2001d
	s_add_i32 s15, s13, s6
	s_sext_i32_i16 s6, s15
	s_and_b32 s15, s15, 0xfffc
	s_sub_i32 s13, s13, s15
	s_sext_i32_i16 s13, s13
	s_lshr_b32 s6, s6, 2
	s_add_i32 s22, s14, s13
	s_ashr_i32 s23, s22, 31
	s_bfe_i64 s[16:17], s[6:7], 0x100000
	s_lshl_b64 s[14:15], s[22:23], 20
	s_lshl_b64 s[16:17], s[16:17], 20
	s_add_u32 s26, s34, s16
	s_addc_u32 s27, s35, s17
	s_add_i32 s23, s36, 0
	s_add_i32 m0, s23, 0x10000
	v_lshl_or_b32 v130, v6, 12, v3
	global_load_lds_dwordx4 v132, s[26:27]
	s_add_i32 m0, s23, 0x12000
	s_add_u32 s24, s30, s14
	global_load_lds_dwordx4 v136, s[26:27]
	s_addc_u32 s25, s31, s15
	s_mov_b32 m0, s23
	s_add_i32 s39, s23, 0x2000
	v_lshl_or_b32 v134, v5, 12, v3
	global_load_lds_dwordx4 v130, s[24:25]
	s_mov_b32 m0, s39
	s_add_u32 s14, s26, 0x80000
	global_load_lds_dwordx4 v134, s[24:25]
	s_addc_u32 s15, s27, 0
	s_add_i32 m0, s23, 0x14000
	v_mov_b32_e32 v133, 0
	global_load_lds_dwordx4 v132, s[14:15]
	s_add_i32 m0, s23, 0x16000
	v_mov_b32_e32 v137, v133
	global_load_lds_dwordx4 v136, s[14:15]
	s_add_u32 s14, s24, 0x80000
	s_addc_u32 s15, s25, 0
	s_add_i32 s40, s23, 0x4000
	s_mov_b32 m0, s40
	s_add_i32 s41, s23, 0x6000
	global_load_lds_dwordx4 v130, s[14:15]
	s_mov_b32 m0, s41
	v_mov_b32_e32 v131, v133
	global_load_lds_dwordx4 v134, s[14:15]
	v_mov_b32_e32 v135, v133
	s_mov_b32 s42, 0
	v_lshl_add_u64 v[8:9], s[26:27], 0, v[132:133]
	v_lshl_add_u64 v[6:7], s[26:27], 0, v[136:137]
	v_lshl_add_u64 v[4:5], s[24:25], 0, v[130:131]
	s_cmp_lg_u32 s7, 1
	v_lshl_add_u64 v[2:3], s[24:25], 0, v[134:135]
	s_cbranch_scc1 .LBB0_478
	s_barrier
.LBB0_478:
	s_ashr_i32 s43, s74, 31
	s_add_u32 s10, s10, 0x18dcc000
	s_addc_u32 s11, s11, 0
	s_lshl_b32 s12, s12, 5
	s_and_b32 s17, s12, 0x60
	s_mov_b64 s[12:13], 0x80
	s_add_i32 m0, s23, 0x18000
	v_lshl_add_u64 v[8:9], v[8:9], 0, s[12:13]
	s_lshl_b32 s16, s7, 13
	s_lshl_b32 s18, s17, 7
	s_waitcnt vmcnt(4)
	s_barrier
	global_load_lds_dwordx4 v[8:9], off
	v_lshl_add_u64 v[6:7], v[6:7], 0, s[12:13]
	s_add_i32 m0, s23, 0x1a000
	s_add_i32 s44, s23, 0x8000
	s_add_i32 s45, s23, 0xa000
	global_load_lds_dwordx4 v[6:7], off
	v_lshl_add_u64 v[4:5], v[4:5], 0, s[12:13]
	s_mov_b32 m0, s44
	s_add_u32 s14, s26, 0x80080
	global_load_lds_dwordx4 v[4:5], off
	v_lshl_add_u64 v[2:3], v[2:3], 0, s[12:13]
	s_mov_b32 m0, s45
	s_addc_u32 s15, s27, 0
	global_load_lds_dwordx4 v[2:3], off
	s_add_i32 m0, s23, 0x1c000
	v_lshl_add_u64 v[2:3], s[14:15], 0, v[132:133]
	global_load_lds_dwordx4 v[2:3], off
	v_lshl_add_u64 v[2:3], s[14:15], 0, v[136:137]
	s_add_i32 m0, s23, 0x1e000
	s_sext_i32_i16 s50, s6
	global_load_lds_dwordx4 v[2:3], off
	v_and_b32_e32 v2, 15, v1
	v_lshlrev_b32_e32 v3, 1, v13
	v_lshlrev_b32_e32 v4, 6, v1
	s_movk_i32 s6, 0x3c0
	v_lshlrev_b32_e32 v5, 2, v1
	v_and_or_b32 v4, v4, s6, v3
	v_and_b32_e32 v5, 32, v5
	v_lshl_or_b32 v148, s7, 6, v2
	v_lshl_or_b32 v2, v2, 6, v3
	v_lshlrev_b32_e32 v3, 9, v1
	v_bitop3_b32 v149, s18, v4, v5 bitop3:0xf6
	v_and_b32_e32 v3, 0x70000, v3
	v_lshlrev_b32_e32 v4, 12, v12
	v_or3_b32 v3, v10, v3, v4
	v_add_u32_e32 v138, v3, v11
	v_lshlrev_b32_e32 v3, 5, v14
	s_waitcnt vmcnt(6)
	v_and_b32_e32 v3, 0xf0000, v3
	v_bitop3_b32 v2, v2, s16, v5 bitop3:0xde
	v_or3_b32 v3, v10, v3, v4
	s_add_i32 s47, 0, 0x10000
	s_add_i32 s48, 0, 0x14000
	s_mov_b32 s46, s74
	v_or_b32_e32 v150, s17, v13
	v_mul_u32_u24_e32 v252, 0x2c00, v148
	v_lshl_add_u32 v252, v150, 1, v252
	v_mov_b32_e32 v139, v133
	v_add_u32_e32 v140, v3, v11
	v_mov_b32_e32 v141, v133
	v_mov_b64_e32 v[142:143], 0xb00
	v_mov_b64_e32 v[144:145], 0xaff
	v_add_u32_e32 v151, s47, v149
	v_add_u32_e32 v152, 0, v2
	v_add_u32_e32 v153, s48, v149
	s_movk_i32 s49, 0x2c00
	s_barrier

; #define PG8_STAGE(bufoff, gbase, voff) do { _Pragma("unroll") for (int _i = 0; _i < 2; ++_i) \
;         __builtin_amdgcn_global_load_lds((const unsigned*)((const char*)(gbase) + (voff)[_i]), (PG8_LAS unsigned*)(lds + (bufoff) + ldsw + _i * 8192), 16, 0, 0); } while (0)
; #define PG8_LDA(dst, b, h) do { _Pragma("unroll") for (int m = 0; m < 4; ++m) _Pragma("unroll") for (int k = 0; k < 2; ++k) dst[m][k] = *(const PG8_LAS bf16x8*)(lds + PG8_SA(b, h) + aoff + m * 2048 + k * 1024); } while (0)
; #define PG8_LDB(dst, b, h) do { _Pragma("unroll") for (int n = 0; n < 2; ++n) _Pragma("unroll") for (int k = 0; k < 2; ++k) dst[n][k] = *(const PG8_LAS bf16x8*)(lds + PG8_SB(b, h) + boff + n * 2048 + k * 1024); } while (0)
; #define PG8_MMA(ai, bj, At, Bt) do { __builtin_amdgcn_s_setprio(1); _Pragma("unroll") for (int m = 0; m < 4; ++m) _Pragma("unroll") for (int n = 0; n < 2; ++n) _Pragma("unroll") for (int k = 0; k < 2; ++k) \
;         acc[ai][bj][m][n] = __builtin_amdgcn_mfma_f32_16x16x32_bf16(Bt[n][k], At[m][k], acc[ai][bj][m][n], 0, 0, 0); __builtin_amdgcn_s_setprio(0); } while (0)
; #define PG8_WAIT_V(n) asm volatile("s_waitcnt vmcnt(" #n ")" ::: "memory")
; #define PG8_WAIT_L(n) asm volatile("s_waitcnt lgkmcnt(" #n ")" ::: "memory")
; #define PG8_BAR __builtin_amdgcn_s_barrier()
; #define PG8_SCHED __builtin_amdgcn_sched_barrier(0)
; template <class Epi, class Sched>
; __device__ __forceinline__ void gemm_phase(PG8_LAS unsigned char* lds, const Gemm g, const Sched& S, const Epi& E) {
;     ...
;             PG8_LDB(B0, 0, 0); PG8_SCHED; PG8_LDA(At, 0, 0); PG8_STAGE(PG8_SA(1, 1), a1 + hstepA, voffA);
;             PG8_WAIT_L(8); PG8_BAR; PG8_WAIT_L(0); PG8_MMA(0, 0, At, B0); PG8_BAR; PG8_SCHED;
;             PG8_LDB(B1, 0, 1); PG8_STAGE(PG8_SB(0, 0), b2, voffB);
;             PG8_BAR; PG8_WAIT_L(0); PG8_MMA(0, 1, At, B1); PG8_BAR;
;             PG8_LDA(At, 0, 1); PG8_STAGE(PG8_SA(0, 0), a2, voffA);
;             PG8_BAR; PG8_WAIT_L(0); PG8_MMA(1, 0, At, B0); PG8_BAR; PG8_SCHED;
;             PG8_STAGE(PG8_SB(0, 1), b2 + hstepB, voffB);
;             PG8_WAIT_V(6); PG8_BAR; PG8_MMA(1, 1, At, B1); PG8_BAR;
.LBB0_482:
	ds_read_b128 v[154:157], v151
	ds_read_b128 v[158:161], v151 offset:1024
	ds_read_b128 v[162:165], v151 offset:2048
	ds_read_b128 v[166:169], v151 offset:3072
	s_add_u32 s26, s24, 0xfff80080
	s_addc_u32 s27, s25, -1
	s_cmp_eq_u32 s55, 28
	s_cselect_b32 s29, s17, s27
	s_cselect_b32 s28, s51, s26
	s_cselect_b32 s27, s15, s54
	s_cselect_b32 s26, s52, s53
	v_lshl_add_u64 v[146:147], s[24:25], 0, v[138:139]
	s_add_i32 m0, s23, 0xc000
	ds_read_b128 v[170:173], v152
	ds_read_b128 v[174:177], v152 offset:1024
	ds_read_b128 v[178:181], v152 offset:2048
	ds_read_b128 v[182:185], v152 offset:3072
	ds_read_b128 v[186:189], v152 offset:4096
	ds_read_b128 v[190:193], v152 offset:5120
	ds_read_b128 v[194:197], v152 offset:6144
	ds_read_b128 v[198:201], v152 offset:7168
	global_load_lds_dwordx4 v[146:147], off
	v_lshl_add_u64 v[146:147], s[24:25], 0, v[140:141]
	s_add_i32 m0, s23, 0xe000
	s_nop 0
	global_load_lds_dwordx4 v[146:147], off
	s_waitcnt lgkmcnt(8)
	s_barrier
	s_waitcnt lgkmcnt(0)
	s_setprio 1
	s_waitcnt lgkmcnt(0)
	v_mfma_f32_16x16x32_bf16 v[126:129], v[154:157], v[170:173], v[126:129]
	v_mfma_f32_16x16x32_bf16 v[122:125], v[162:165], v[170:173], v[122:125]
	v_mfma_f32_16x16x32_bf16 v[110:113], v[154:157], v[178:181], v[110:113]
	v_mfma_f32_16x16x32_bf16 v[106:109], v[162:165], v[178:181], v[106:109]
	v_mfma_f32_16x16x32_bf16 v[94:97], v[154:157], v[186:189], v[94:97]
	v_mfma_f32_16x16x32_bf16 v[90:93], v[162:165], v[186:189], v[90:93]
	v_mfma_f32_16x16x32_bf16 v[78:81], v[154:157], v[194:197], v[78:81]
	v_mfma_f32_16x16x32_bf16 v[74:77], v[162:165], v[194:197], v[74:77]
	v_mfma_f32_16x16x32_bf16 v[126:129], v[158:161], v[174:177], v[126:129]
	v_mfma_f32_16x16x32_bf16 v[122:125], v[166:169], v[174:177], v[122:125]
	v_mfma_f32_16x16x32_bf16 v[110:113], v[158:161], v[182:185], v[110:113]
	v_mfma_f32_16x16x32_bf16 v[106:109], v[166:169], v[182:185], v[106:109]
	v_mfma_f32_16x16x32_bf16 v[94:97], v[158:161], v[190:193], v[94:97]
	v_mfma_f32_16x16x32_bf16 v[90:93], v[166:169], v[190:193], v[90:93]
	v_mfma_f32_16x16x32_bf16 v[78:81], v[158:161], v[198:201], v[78:81]
	v_mfma_f32_16x16x32_bf16 v[74:77], v[166:169], v[198:201], v[74:77]
	s_setprio 0
	s_barrier
	s_add_i32 s56, s47, s36
	v_lshl_add_u64 v[146:147], s[26:27], 0, v[132:133]
	s_mov_b32 m0, s56
	ds_read_b128 v[202:205], v153
	ds_read_b128 v[206:209], v153 offset:1024
	ds_read_b128 v[210:213], v153 offset:2048
	ds_read_b128 v[214:217], v153 offset:3072
	global_load_lds_dwordx4 v[146:147], off
	v_lshl_add_u64 v[218:219], s[26:27], 0, v[136:137]
	s_add_i32 m0, s56, 0x2000
	s_nop 0
	global_load_lds_dwordx4 v[218:219], off
	s_barrier
	s_waitcnt lgkmcnt(0)
	s_setprio 1
	s_waitcnt lgkmcnt(0)
	v_mfma_f32_16x16x32_bf16 v[118:121], v[202:205], v[170:173], v[118:121]
	v_mfma_f32_16x16x32_bf16 v[114:117], v[210:213], v[170:173], v[114:117]
	v_mfma_f32_16x16x32_bf16 v[102:105], v[202:205], v[178:181], v[102:105]
	v_mfma_f32_16x16x32_bf16 v[98:101], v[210:213], v[178:181], v[98:101]
	v_mfma_f32_16x16x32_bf16 v[86:89], v[202:205], v[186:189], v[86:89]
	v_mfma_f32_16x16x32_bf16 v[82:85], v[210:213], v[186:189], v[82:85]
	v_mfma_f32_16x16x32_bf16 v[70:73], v[202:205], v[194:197], v[70:73]
	v_mfma_f32_16x16x32_bf16 v[66:69], v[210:213], v[194:197], v[66:69]
	v_mfma_f32_16x16x32_bf16 v[118:121], v[206:209], v[174:177], v[118:121]
	v_mfma_f32_16x16x32_bf16 v[114:117], v[214:217], v[174:177], v[114:117]
	v_mfma_f32_16x16x32_bf16 v[102:105], v[206:209], v[182:185], v[102:105]
	v_mfma_f32_16x16x32_bf16 v[98:101], v[214:217], v[182:185], v[98:101]
	v_mfma_f32_16x16x32_bf16 v[86:89], v[206:209], v[190:193], v[86:89]
	v_mfma_f32_16x16x32_bf16 v[82:85], v[214:217], v[190:193], v[82:85]
	v_mfma_f32_16x16x32_bf16 v[70:73], v[206:209], v[198:201], v[70:73]
	v_mfma_f32_16x16x32_bf16 v[66:69], v[214:217], v[198:201], v[66:69]
	s_setprio 0
	s_mov_b32 m0, s23
	v_lshl_add_u64 v[220:221], s[28:29], 0, v[130:131]
	s_barrier
	ds_read_b128 v[170:173], v152 offset:16384
	ds_read_b128 v[174:177], v152 offset:17408
	ds_read_b128 v[178:181], v152 offset:18432
	ds_read_b128 v[182:185], v152 offset:19456
	ds_read_b128 v[186:189], v152 offset:20480
	ds_read_b128 v[190:193], v152 offset:21504
	ds_read_b128 v[194:197], v152 offset:22528
	ds_read_b128 v[198:201], v152 offset:23552
	global_load_lds_dwordx4 v[220:221], off
	v_lshl_add_u64 v[222:223], s[28:29], 0, v[134:135]
	s_mov_b32 m0, s39
	s_nop 0
	global_load_lds_dwordx4 v[222:223], off
	s_barrier
	s_waitcnt lgkmcnt(0)
	s_setprio 1
	s_waitcnt lgkmcnt(0)
	v_mfma_f32_16x16x32_bf16 v[62:65], v[154:157], v[170:173], v[62:65]
	v_mfma_f32_16x16x32_bf16 v[58:61], v[162:165], v[170:173], v[58:61]
	v_mfma_f32_16x16x32_bf16 v[46:49], v[154:157], v[178:181], v[46:49]
	v_mfma_f32_16x16x32_bf16 v[42:45], v[162:165], v[178:181], v[42:45]
	v_mfma_f32_16x16x32_bf16 v[30:33], v[154:157], v[186:189], v[30:33]
	v_mfma_f32_16x16x32_bf16 v[26:29], v[162:165], v[186:189], v[26:29]
	v_mfma_f32_16x16x32_bf16 v[14:17], v[154:157], v[194:197], v[14:17]
	v_mfma_f32_16x16x32_bf16 v[10:13], v[162:165], v[194:197], v[10:13]
	v_mfma_f32_16x16x32_bf16 v[62:65], v[158:161], v[174:177], v[62:65]
	v_mfma_f32_16x16x32_bf16 v[58:61], v[166:169], v[174:177], v[58:61]
	v_mfma_f32_16x16x32_bf16 v[46:49], v[158:161], v[182:185], v[46:49]
	v_mfma_f32_16x16x32_bf16 v[42:45], v[166:169], v[182:185], v[42:45]
	v_mfma_f32_16x16x32_bf16 v[30:33], v[158:161], v[190:193], v[30:33]
	v_mfma_f32_16x16x32_bf16 v[26:29], v[166:169], v[190:193], v[26:29]
	v_mfma_f32_16x16x32_bf16 v[14:17], v[158:161], v[198:201], v[14:17]
	v_mfma_f32_16x16x32_bf16 v[10:13], v[166:169], v[198:201], v[10:13]
	s_setprio 0
	s_barrier
	s_add_u32 s56, s26, 0x80000
	s_addc_u32 s57, s27, 0
	s_add_i32 s58, s48, s36
	v_lshl_add_u64 v[154:155], s[56:57], 0, v[132:133]
	s_mov_b32 m0, s58
	s_nop 0
	global_load_lds_dwordx4 v[154:155], off
	v_lshl_add_u64 v[154:155], s[56:57], 0, v[136:137]
	s_add_i32 m0, s58, 0x2000
	s_nop 0
	global_load_lds_dwordx4 v[154:155], off
	s_waitcnt vmcnt(6)
	s_cmp_gt_i32 s55, 4
	s_cbranch_scc1 .Ltk482_4d
	s_cmp_eq_u64 s[98:99], 0
	s_cbranch_scc1 .Ltk482_4d
	s_cmp_eq_u32 s55, -2
	s_cbranch_scc1 .Ltk482_k1
	s_cmp_eq_u32 s55, 0
	s_cbranch_scc1 .Ltk482_k3
	s_cmp_eq_u32 s55, 2
	s_cbranch_scc1 .Ltk482_k5
	s_add_u32 s100, s98, 0x1e4000
	s_addc_u32 s101, s99, 0
	global_store_dwordx4 v252, v[248:251], s[100:101]
	s_branch .Ltk482_4d
; #define PG8_STAGE(bufoff, gbase, voff) do { _Pragma("unroll") for (int _i = 0; _i < 2; ++_i) \
;         __builtin_amdgcn_global_load_lds((const unsigned*)((const char*)(gbase) + (voff)[_i]), (PG8_LAS unsigned*)(lds + (bufoff) + ldsw + _i * 8192), 16, 0, 0); } while (0)
; #define PG8_LDA(dst, b, h) do { _Pragma("unroll") for (int m = 0; m < 4; ++m) _Pragma("unroll") for (int k = 0; k < 2; ++k) dst[m][k] = *(const PG8_LAS bf16x8*)(lds + PG8_SA(b, h) + aoff + m * 2048 + k * 1024); } while (0)
; #define PG8_LDB(dst, b, h) do { _Pragma("unroll") for (int n = 0; n < 2; ++n) _Pragma("unroll") for (int k = 0; k < 2; ++k) dst[n][k] = *(const PG8_LAS bf16x8*)(lds + PG8_SB(b, h) + boff + n * 2048 + k * 1024); } while (0)
; #define PG8_MMA(ai, bj, At, Bt) do { __builtin_amdgcn_s_setprio(1); _Pragma("unroll") for (int m = 0; m < 4; ++m) _Pragma("unroll") for (int n = 0; n < 2; ++n) _Pragma("unroll") for (int k = 0; k < 2; ++k) \
;         acc[ai][bj][m][n] = __builtin_amdgcn_mfma_f32_16x16x32_bf16(Bt[n][k], At[m][k], acc[ai][bj][m][n], 0, 0, 0); __builtin_amdgcn_s_setprio(0); } while (0)
; #define PG8_WAIT_V(n) asm volatile("s_waitcnt vmcnt(" #n ")" ::: "memory")
; #define PG8_WAIT_L(n) asm volatile("s_waitcnt lgkmcnt(" #n ")" ::: "memory")
; #define PG8_BAR __builtin_amdgcn_s_barrier()
; #define PG8_SCHED __builtin_amdgcn_sched_barrier(0)
; template <class Epi, class Sched>
; __device__ __forceinline__ void gemm_phase(PG8_LAS unsigned char* lds, const Gemm g, const Sched& S, const Epi& E) {
;     ...
;             PG8_WAIT_V(6); PG8_BAR; PG8_MMA(1, 1, At, B1); PG8_BAR;
;             PG8_LDB(B0, 1, 0); PG8_SCHED; PG8_LDA(At, 1, 0); PG8_STAGE(PG8_SA(0, 1), a2 + hstepA, voffA);
;             PG8_WAIT_L(8); PG8_BAR; PG8_WAIT_L(0); PG8_MMA(0, 0, At, B0); PG8_BAR; PG8_SCHED;
;             PG8_LDB(B1, 1, 1); PG8_STAGE(PG8_SB(1, 0), b3, voffB);
;             PG8_BAR; PG8_WAIT_L(0); PG8_MMA(0, 1, At, B1); PG8_BAR;
.Ltk482_k1:
	s_add_u32 s100, s98, 0x2c000
	s_addc_u32 s101, s99, 0
	global_store_dwordx4 v252, v[224:227], s[100:101]
	s_branch .Ltk482_4d
.Ltk482_k3:
	s_add_u32 s100, s98, 0x84000
	s_addc_u32 s101, s99, 0
	global_store_dwordx4 v252, v[232:235], s[100:101]
	s_branch .Ltk482_4d
.Ltk482_k5:
	s_add_u32 s100, s98, 0x18c000
	s_addc_u32 s101, s99, 0
	global_store_dwordx4 v252, v[240:243], s[100:101]
.Ltk482_4d:
	s_barrier
	s_setprio 1
	v_mfma_f32_16x16x32_bf16 v[54:57], v[202:205], v[170:173], v[54:57]
	v_mfma_f32_16x16x32_bf16 v[50:53], v[210:213], v[170:173], v[50:53]
	v_mfma_f32_16x16x32_bf16 v[38:41], v[202:205], v[178:181], v[38:41]
	v_mfma_f32_16x16x32_bf16 v[34:37], v[210:213], v[178:181], v[34:37]
	v_mfma_f32_16x16x32_bf16 v[22:25], v[202:205], v[186:189], v[22:25]
	v_mfma_f32_16x16x32_bf16 v[18:21], v[210:213], v[186:189], v[18:21]
	v_mfma_f32_16x16x32_bf16 v[6:9], v[202:205], v[194:197], v[6:9]
	v_mfma_f32_16x16x32_bf16 v[2:5], v[210:213], v[194:197], v[2:5]
	v_mfma_f32_16x16x32_bf16 v[54:57], v[206:209], v[174:177], v[54:57]
	v_mfma_f32_16x16x32_bf16 v[50:53], v[214:217], v[174:177], v[50:53]
	v_mfma_f32_16x16x32_bf16 v[38:41], v[206:209], v[182:185], v[38:41]
	v_mfma_f32_16x16x32_bf16 v[34:37], v[214:217], v[182:185], v[34:37]
	v_mfma_f32_16x16x32_bf16 v[22:25], v[206:209], v[190:193], v[22:25]
	v_mfma_f32_16x16x32_bf16 v[18:21], v[214:217], v[190:193], v[18:21]
	v_mfma_f32_16x16x32_bf16 v[6:9], v[206:209], v[198:201], v[6:9]
	v_mfma_f32_16x16x32_bf16 v[2:5], v[214:217], v[198:201], v[2:5]
	s_setprio 0
	s_add_i32 s56, 0, 0x18000
	v_add_u32_e32 v166, s56, v149
	s_barrier
	ds_read_b128 v[154:157], v166
	ds_read_b128 v[158:161], v166 offset:1024
	ds_read_b128 v[162:165], v166 offset:2048
	ds_read_b128 v[166:169], v166 offset:3072
	s_add_u32 s28, s28, 0x80000
	s_addc_u32 s29, s29, 0
	s_mov_b32 m0, s40
	v_lshl_add_u64 v[202:203], s[28:29], 0, v[130:131]
	ds_read_b128 v[170:173], v152 offset:32768
	ds_read_b128 v[174:177], v152 offset:33792
	ds_read_b128 v[178:181], v152 offset:34816
	ds_read_b128 v[182:185], v152 offset:35840
	ds_read_b128 v[186:189], v152 offset:36864
	ds_read_b128 v[190:193], v152 offset:37888
	ds_read_b128 v[194:197], v152 offset:38912
	ds_read_b128 v[198:201], v152 offset:39936
	global_load_lds_dwordx4 v[202:203], off
	v_lshl_add_u64 v[202:203], s[28:29], 0, v[134:135]
	s_mov_b32 m0, s41
	s_nop 0
	global_load_lds_dwordx4 v[202:203], off
	s_waitcnt lgkmcnt(8)
	s_barrier
	s_waitcnt lgkmcnt(0)
	s_setprio 1
	s_waitcnt lgkmcnt(0)
	v_mfma_f32_16x16x32_bf16 v[126:129], v[154:157], v[170:173], v[126:129]
	v_mfma_f32_16x16x32_bf16 v[122:125], v[162:165], v[170:173], v[122:125]
	v_mfma_f32_16x16x32_bf16 v[110:113], v[154:157], v[178:181], v[110:113]
	v_mfma_f32_16x16x32_bf16 v[106:109], v[162:165], v[178:181], v[106:109]
	v_mfma_f32_16x16x32_bf16 v[94:97], v[154:157], v[186:189], v[94:97]
	v_mfma_f32_16x16x32_bf16 v[90:93], v[162:165], v[186:189], v[90:93]
	v_mfma_f32_16x16x32_bf16 v[78:81], v[154:157], v[194:197], v[78:81]
	v_mfma_f32_16x16x32_bf16 v[74:77], v[162:165], v[194:197], v[74:77]
	v_mfma_f32_16x16x32_bf16 v[126:129], v[158:161], v[174:177], v[126:129]
	v_mfma_f32_16x16x32_bf16 v[122:125], v[166:169], v[174:177], v[122:125]
	v_mfma_f32_16x16x32_bf16 v[110:113], v[158:161], v[182:185], v[110:113]
	v_mfma_f32_16x16x32_bf16 v[106:109], v[166:169], v[182:185], v[106:109]
	v_mfma_f32_16x16x32_bf16 v[94:97], v[158:161], v[190:193], v[94:97]
	v_mfma_f32_16x16x32_bf16 v[90:93], v[166:169], v[190:193], v[90:93]
	v_mfma_f32_16x16x32_bf16 v[78:81], v[158:161], v[198:201], v[78:81]
	v_mfma_f32_16x16x32_bf16 v[74:77], v[166:169], v[198:201], v[74:77]
	s_setprio 0
	s_barrier
	s_add_i32 s28, 0, 0x1c000
	s_add_i32 s29, s56, s36
	v_add_u32_e32 v214, s28, v149
	v_lshl_add_u64 v[146:147], v[146:147], 0, s[12:13]
	s_mov_b32 m0, s29
	ds_read_b128 v[202:205], v214
	ds_read_b128 v[206:209], v214 offset:1024
	ds_read_b128 v[210:213], v214 offset:2048
	ds_read_b128 v[214:217], v214 offset:3072
	global_load_lds_dwordx4 v[146:147], off
	v_lshl_add_u64 v[146:147], v[218:219], 0, s[12:13]
	s_add_i32 m0, s29, 0x2000
	s_nop 0
	global_load_lds_dwordx4 v[146:147], off
	s_barrier
	s_waitcnt lgkmcnt(0)
	s_setprio 1
	s_waitcnt lgkmcnt(0)
	v_mfma_f32_16x16x32_bf16 v[118:121], v[202:205], v[170:173], v[118:121]
	v_mfma_f32_16x16x32_bf16 v[114:117], v[210:213], v[170:173], v[114:117]
	v_mfma_f32_16x16x32_bf16 v[102:105], v[202:205], v[178:181], v[102:105]
	v_mfma_f32_16x16x32_bf16 v[98:101], v[210:213], v[178:181], v[98:101]
	v_mfma_f32_16x16x32_bf16 v[86:89], v[202:205], v[186:189], v[86:89]
	v_mfma_f32_16x16x32_bf16 v[82:85], v[210:213], v[186:189], v[82:85]
	v_mfma_f32_16x16x32_bf16 v[70:73], v[202:205], v[194:197], v[70:73]
	v_mfma_f32_16x16x32_bf16 v[66:69], v[210:213], v[194:197], v[66:69]
	v_mfma_f32_16x16x32_bf16 v[118:121], v[206:209], v[174:177], v[118:121]
	v_mfma_f32_16x16x32_bf16 v[114:117], v[214:217], v[174:177], v[114:117]
	v_mfma_f32_16x16x32_bf16 v[102:105], v[206:209], v[182:185], v[102:105]
	v_mfma_f32_16x16x32_bf16 v[98:101], v[214:217], v[182:185], v[98:101]
	v_mfma_f32_16x16x32_bf16 v[86:89], v[206:209], v[190:193], v[86:89]
	v_mfma_f32_16x16x32_bf16 v[82:85], v[214:217], v[190:193], v[82:85]
	v_mfma_f32_16x16x32_bf16 v[70:73], v[206:209], v[198:201], v[70:73]
	v_mfma_f32_16x16x32_bf16 v[66:69], v[214:217], v[198:201], v[66:69]
	s_setprio 0
	s_mov_b32 m0, s44
	v_lshl_add_u64 v[146:147], v[220:221], 0, s[12:13]
	s_barrier
; #define PG8_STAGE(bufoff, gbase, voff) do { _Pragma("unroll") for (int _i = 0; _i < 2; ++_i) \
;         __builtin_amdgcn_global_load_lds((const unsigned*)((const char*)(gbase) + (voff)[_i]), (PG8_LAS unsigned*)(lds + (bufoff) + ldsw + _i * 8192), 16, 0, 0); } while (0)
; #define PG8_LDA(dst, b, h) do { _Pragma("unroll") for (int m = 0; m < 4; ++m) _Pragma("unroll") for (int k = 0; k < 2; ++k) dst[m][k] = *(const PG8_LAS bf16x8*)(lds + PG8_SA(b, h) + aoff + m * 2048 + k * 1024); } while (0)
; #define PG8_MMA(ai, bj, At, Bt) do { __builtin_amdgcn_s_setprio(1); _Pragma("unroll") for (int m = 0; m < 4; ++m) _Pragma("unroll") for (int n = 0; n < 2; ++n) _Pragma("unroll") for (int k = 0; k < 2; ++k) \
;         acc[ai][bj][m][n] = __builtin_amdgcn_mfma_f32_16x16x32_bf16(Bt[n][k], At[m][k], acc[ai][bj][m][n], 0, 0, 0); __builtin_amdgcn_s_setprio(0); } while (0)
; #define PG8_WAIT_V(n) asm volatile("s_waitcnt vmcnt(" #n ")" ::: "memory")
; #define PG8_WAIT_L(n) asm volatile("s_waitcnt lgkmcnt(" #n ")" ::: "memory")
; #define PG8_BAR __builtin_amdgcn_s_barrier()
; #define PG8_SCHED __builtin_amdgcn_sched_barrier(0)
; DI float silu_(float x) { return x * sigmoid_(x); }
; template <class Epi, class Sched>
; __device__ __forceinline__ void gemm_phase(PG8_LAS unsigned char* lds, const Gemm g, const Sched& S, const Epi& E) {
;     ...
;             PG8_LDA(At, 1, 1); PG8_STAGE(PG8_SA(1, 0), a3, voffA);
;             PG8_BAR; PG8_WAIT_L(0); PG8_MMA(1, 0, At, B0); PG8_BAR; PG8_SCHED;
;             PG8_STAGE(PG8_SB(1, 1), b3 + hstepB, voffB);
;             PG8_WAIT_V(6); PG8_BAR; PG8_MMA(1, 1, At, B1); PG8_BAR;
;         }
;     DI void operator()(const f32x4 (&acc)[2][2][4][2], const Unit& u, int wr, int wc, int fr, int fq) const {
;         const int row0 = u.pm * 256 + wr * 64 + fr, col0 = u.pn * 128 + wc * 32 + 8 * fq;
; #pragma unroll
;         for (int ai = 0; ai < 2; ++ai)
; #pragma unroll
;             for (int m = 0; m < 4; ++m) { bf16_t* rowp = O + (size_t)(row0 + ai * 128 + m * 16) * ldc + col0;
;                 f32x4 v0, v1;
; #pragma unroll
;                 for (int j = 0; j < 4; ++j) { v0[j] = silu_(acc[ai][0][m][0][j]) * acc[ai][1][m][0][j]; v1[j] = silu_(acc[ai][0][m][1][j]) * acc[ai][1][m][1][j]; }
	ds_read_b128 v[170:173], v152 offset:49152
	ds_read_b128 v[174:177], v152 offset:50176
	ds_read_b128 v[178:181], v152 offset:51200
	ds_read_b128 v[182:185], v152 offset:52224
	ds_read_b128 v[186:189], v152 offset:53248
	ds_read_b128 v[190:193], v152 offset:54272
	ds_read_b128 v[194:197], v152 offset:55296
	ds_read_b128 v[198:201], v152 offset:56320
	global_load_lds_dwordx4 v[146:147], off
	v_lshl_add_u64 v[146:147], v[222:223], 0, s[12:13]
	s_mov_b32 m0, s45
	s_nop 0
	global_load_lds_dwordx4 v[146:147], off
	s_barrier
	s_waitcnt lgkmcnt(0)
	s_setprio 1
	s_waitcnt lgkmcnt(0)
	v_mfma_f32_16x16x32_bf16 v[62:65], v[154:157], v[170:173], v[62:65]
	v_mfma_f32_16x16x32_bf16 v[58:61], v[162:165], v[170:173], v[58:61]
	v_mfma_f32_16x16x32_bf16 v[46:49], v[154:157], v[178:181], v[46:49]
	v_mfma_f32_16x16x32_bf16 v[42:45], v[162:165], v[178:181], v[42:45]
	v_mfma_f32_16x16x32_bf16 v[30:33], v[154:157], v[186:189], v[30:33]
	v_mfma_f32_16x16x32_bf16 v[26:29], v[162:165], v[186:189], v[26:29]
	v_mfma_f32_16x16x32_bf16 v[14:17], v[154:157], v[194:197], v[14:17]
	v_mfma_f32_16x16x32_bf16 v[10:13], v[162:165], v[194:197], v[10:13]
	v_mfma_f32_16x16x32_bf16 v[62:65], v[158:161], v[174:177], v[62:65]
	v_mfma_f32_16x16x32_bf16 v[58:61], v[166:169], v[174:177], v[58:61]
	v_mfma_f32_16x16x32_bf16 v[46:49], v[158:161], v[182:185], v[46:49]
	v_mfma_f32_16x16x32_bf16 v[42:45], v[166:169], v[182:185], v[42:45]
	v_mfma_f32_16x16x32_bf16 v[30:33], v[158:161], v[190:193], v[30:33]
	v_mfma_f32_16x16x32_bf16 v[26:29], v[166:169], v[190:193], v[26:29]
	v_mfma_f32_16x16x32_bf16 v[14:17], v[158:161], v[198:201], v[14:17]
	v_mfma_f32_16x16x32_bf16 v[10:13], v[166:169], v[198:201], v[10:13]
	s_setprio 0
	s_barrier
	s_add_u32 s26, s26, 0x80080
	s_addc_u32 s27, s27, 0
	s_add_i32 s28, s28, s36
	v_lshl_add_u64 v[146:147], s[26:27], 0, v[132:133]
	s_mov_b32 m0, s28
	s_nop 0
	global_load_lds_dwordx4 v[146:147], off
	v_lshl_add_u64 v[146:147], s[26:27], 0, v[136:137]
	s_add_i32 m0, s28, 0x2000
	s_nop 0
	global_load_lds_dwordx4 v[146:147], off
	s_waitcnt vmcnt(6)
	s_cmp_gt_i32 s55, 2
	s_cbranch_scc1 .Ltk482_8d
	s_cmp_eq_u64 s[98:99], 0
	s_cbranch_scc1 .Ltk482_8d
	s_cmp_eq_u32 s55, -2
	s_cbranch_scc1 .Ltk482_k2
	s_cmp_eq_u32 s55, 0
	s_cbranch_scc1 .Ltk482_k4
	s_add_u32 s100, s98, 0x1b8000
	s_addc_u32 s101, s99, 0
	global_store_dwordx4 v252, v[244:247], s[100:101]
	s_branch .Ltk482_8d
.Ltk482_k2:
	s_add_u32 s100, s98, 0x58000
	s_addc_u32 s101, s99, 0
	global_store_dwordx4 v252, v[228:231], s[100:101]
	s_branch .Ltk482_8d
.Ltk482_k4:
	s_add_u32 s100, s98, 0x160000
	s_addc_u32 s101, s99, 0
	global_store_dwordx4 v252, v[236:239], s[100:101]
.Ltk482_8d:
	s_barrier
	s_setprio 1
	v_mfma_f32_16x16x32_bf16 v[54:57], v[202:205], v[170:173], v[54:57]
	v_mfma_f32_16x16x32_bf16 v[50:53], v[210:213], v[170:173], v[50:53]
	v_mfma_f32_16x16x32_bf16 v[38:41], v[202:205], v[178:181], v[38:41]
	v_mfma_f32_16x16x32_bf16 v[34:37], v[210:213], v[178:181], v[34:37]
	v_mfma_f32_16x16x32_bf16 v[22:25], v[202:205], v[186:189], v[22:25]
	v_mfma_f32_16x16x32_bf16 v[18:21], v[210:213], v[186:189], v[18:21]
	v_mfma_f32_16x16x32_bf16 v[6:9], v[202:205], v[194:197], v[6:9]
	v_mfma_f32_16x16x32_bf16 v[2:5], v[210:213], v[194:197], v[2:5]
	v_mfma_f32_16x16x32_bf16 v[54:57], v[206:209], v[174:177], v[54:57]
	v_mfma_f32_16x16x32_bf16 v[50:53], v[214:217], v[174:177], v[50:53]
	v_mfma_f32_16x16x32_bf16 v[38:41], v[206:209], v[182:185], v[38:41]
	v_mfma_f32_16x16x32_bf16 v[34:37], v[214:217], v[182:185], v[34:37]
	v_mfma_f32_16x16x32_bf16 v[22:25], v[206:209], v[190:193], v[22:25]
	v_mfma_f32_16x16x32_bf16 v[18:21], v[214:217], v[190:193], v[18:21]
	v_mfma_f32_16x16x32_bf16 v[6:9], v[206:209], v[198:201], v[6:9]
	v_mfma_f32_16x16x32_bf16 v[2:5], v[214:217], v[198:201], v[2:5]
	s_setprio 0
	s_add_i32 s55, s55, 2
	s_add_u32 s24, s24, 0x100
	s_addc_u32 s25, s25, 0
	s_add_u32 s53, s53, 0x100
	s_addc_u32 s54, s54, 0
	s_cmp_gt_u32 s55, 29
	s_barrier
	s_cbranch_scc0 .LBB0_482
	s_lshl_b32 s100, s22, 8
	s_mul_i32 s100, s100, s49
	s_lshl_b32 s101, s50, 8
	s_add_u32 s100, s100, s101
	s_add_u32 s98, s10, s100
	s_addc_u32 s99, s11, 0
	v_mul_f32_e32 v146, 0xbfb8aa3b, v126
	v_exp_f32_e32 v155, v146
	v_mul_f32_e32 v146, 0xbfb8aa3b, v122
	v_exp_f32_e32 v158, v146
	v_lshl_or_b32 v156, s50, 7, v150
	v_add_f32_e32 v155, 1.0, v155
	v_rcp_f32_e32 v155, v155
	v_add_f32_e32 v158, 1.0, v158
	v_rcp_f32_e32 v160, v158
	v_lshl_add_u32 v154, s22, 8, v148
	v_mul_f32_e32 v126, v126, v155
	v_mul_f32_e32 v118, v126, v118
	v_mul_f32_e32 v126, 0xbfb8aa3b, v127
	v_exp_f32_e32 v126, v126
	v_mul_f32_e32 v155, 0xbfb8aa3b, v123
	v_exp_f32_e32 v155, v155
	v_mul_f32_e32 v122, v122, v160
	v_mul_f32_e32 v122, v122, v114
	v_add_f32_e32 v114, 1.0, v126
	v_rcp_f32_e32 v114, v114
	v_add_f32_e32 v126, 1.0, v155
	v_mul_f32_e32 v155, 0xbfb8aa3b, v128
	v_rcp_f32_e32 v126, v126
	v_exp_f32_e32 v155, v155
	v_mul_f32_e32 v114, v127, v114
	v_mul_f32_e32 v119, v114, v119
	v_mul_f32_e32 v114, v123, v126
	v_add_f32_e32 v123, 1.0, v155
	v_rcp_f32_e32 v123, v123
	v_mul_f32_e32 v126, 0xbfb8aa3b, v124
	v_exp_f32_e32 v126, v126
	v_mul_f32_e32 v127, v114, v115
	v_mul_f32_e32 v114, v128, v123
	v_mul_f32_e32 v115, 0xbfb8aa3b, v129
	v_mul_f32_e32 v123, v114, v120
	v_exp_f32_e32 v115, v115
	v_mul_f32_e32 v120, 0xbfb8aa3b, v125
	v_exp_f32_e32 v120, v120
	v_add_f32_e32 v114, 1.0, v126
	v_rcp_f32_e32 v114, v114
	v_add_f32_e32 v115, 1.0, v115
	v_rcp_f32_e32 v115, v115
	v_add_f32_e32 v120, 1.0, v120
	v_rcp_f32_e32 v120, v120
	v_mul_f32_e32 v114, v124, v114
	v_mul_f32_e32 v124, v114, v116
	v_mul_f32_e32 v114, v129, v115
	v_ashrrev_i32_e32 v157, 31, v156
	v_mov_b64_e32 v[146:147], s[10:11]
; __device__ __forceinline__ unsigned cvt_pk_bf16(float lo, float hi) { unsigned r; asm volatile("v_cvt_pk_bf16_f32 %0, %1, %2" : "=v"(r) : "v"(lo), "v"(hi)); return r; }
; DI float silu_(float x) { return x * sigmoid_(x); }
;     DI void operator()(const f32x4 (&acc)[2][2][4][2], const Unit& u, int wr, int wc, int fr, int fq) const {
;     ...
;         for (int ai = 0; ai < 2; ++ai)
; #pragma unroll
;             for (int m = 0; m < 4; ++m) { bf16_t* rowp = O + (size_t)(row0 + ai * 128 + m * 16) * ldc + col0;
;                 f32x4 v0, v1;
; #pragma unroll
;                 for (int j = 0; j < 4; ++j) { v0[j] = silu_(acc[ai][0][m][0][j]) * acc[ai][1][m][0][j]; v1[j] = silu_(acc[ai][0][m][1][j]) * acc[ai][1][m][1][j]; }
;                 u32x4 w; w.x = pg8::cvt_pk_bf16(v0[0], v0[1]); w.y = pg8::cvt_pk_bf16(v0[2], v0[3]); w.z = pg8::cvt_pk_bf16(v1[0], v1[1]); w.w = pg8::cvt_pk_bf16(v1[2], v1[3]);
;                 *(u32x4*)rowp = w; }
	v_mul_f32_e32 v126, v114, v121
	v_mul_f32_e32 v114, v125, v120
	v_mad_i64_i32 v[158:159], s[24:25], v154, s49, v[146:147]
	v_mul_f32_e32 v125, v114, v117
	v_lshlrev_b64 v[114:115], 1, v[156:157]
	v_lshl_add_u64 v[120:121], v[158:159], 0, v[114:115]
	v_cvt_pk_bf16_f32 v116, v118, v119
	v_cvt_pk_bf16_f32 v117, v123, v126
	v_cvt_pk_bf16_f32 v118, v122, v127
	v_cvt_pk_bf16_f32 v119, v124, v125
	global_store_dwordx4 v[120:121], v[116:119], off
	s_and_b64 vcc, exec, s[6:7]
	s_mov_b32 s50, s14
	v_mul_f32_e32 v116, 0xbfb8aa3b, v110
	v_exp_f32_e32 v116, v116
	v_mul_f32_e32 v117, 0xbfb8aa3b, v106
	v_exp_f32_e32 v117, v117
	v_or_b32_e32 v118, 16, v154
	v_add_f32_e32 v116, 1.0, v116
	v_rcp_f32_e32 v119, v116
	v_add_f32_e32 v116, 1.0, v117
	v_rcp_f32_e32 v120, v116
	v_mad_i64_i32 v[116:117], s[24:25], v118, s49, v[146:147]
	v_mul_f32_e32 v110, v110, v119
	v_mul_f32_e32 v110, v110, v102
	v_mul_f32_e32 v102, v106, v120
	v_mul_f32_e32 v106, 0xbfb8aa3b, v111
	v_exp_f32_e32 v106, v106
	v_mul_f32_e32 v118, 0xbfb8aa3b, v107
	v_mul_f32_e32 v119, v102, v98
	v_exp_f32_e32 v118, v118
	v_add_f32_e32 v98, 1.0, v106
	v_rcp_f32_e32 v98, v98
	v_mul_f32_e32 v106, 0xbfb8aa3b, v112
	v_exp_f32_e32 v106, v106
	v_add_f32_e32 v102, 1.0, v118
	v_mul_f32_e32 v98, v111, v98
	v_rcp_f32_e32 v102, v102
	v_mul_f32_e32 v98, v98, v103
	v_add_f32_e32 v103, 1.0, v106
	v_rcp_f32_e32 v103, v103
	v_mul_f32_e32 v102, v107, v102
	v_mul_f32_e32 v106, 0xbfb8aa3b, v108
	v_mul_f32_e32 v107, v102, v99
	v_mul_f32_e32 v99, v112, v103
	v_exp_f32_e32 v106, v106
	v_mul_f32_e32 v99, v99, v104
	v_mul_f32_e32 v103, 0xbfb8aa3b, v113
	v_mul_f32_e32 v104, 0xbfb8aa3b, v109
	v_exp_f32_e32 v103, v103
	v_exp_f32_e32 v104, v104
	v_add_f32_e32 v102, 1.0, v106
	v_rcp_f32_e32 v102, v102
	v_add_f32_e32 v103, 1.0, v103
	v_add_f32_e32 v104, 1.0, v104
	v_rcp_f32_e32 v103, v103
	v_rcp_f32_e32 v104, v104
	v_mul_f32_e32 v102, v108, v102
	v_mul_f32_e32 v106, v102, v100
	v_mul_f32_e32 v100, v113, v103
	v_mul_f32_e32 v102, v109, v104
	v_mul_f32_e32 v100, v100, v105
	v_mul_f32_e32 v101, v102, v101
	v_lshl_add_u64 v[102:103], v[116:117], 0, v[114:115]
	v_cvt_pk_bf16_f32 v98, v110, v98
	v_cvt_pk_bf16_f32 v99, v99, v100
	v_cvt_pk_bf16_f32 v100, v119, v107
	v_cvt_pk_bf16_f32 v101, v106, v101
	v_mov_b32_e32 v224, v98
	v_mov_b32_e32 v225, v99
	v_mov_b32_e32 v226, v100
	v_mov_b32_e32 v227, v101
	s_mov_b32 s22, s16
	s_mov_b64 s[26:27], s[20:21]
	v_mul_f32_e32 v98, 0xbfb8aa3b, v94
	v_exp_f32_e32 v98, v98
	v_mul_f32_e32 v99, 0xbfb8aa3b, v90
	v_exp_f32_e32 v99, v99
	v_or_b32_e32 v100, 32, v154
	v_add_f32_e32 v98, 1.0, v98
	v_rcp_f32_e32 v101, v98
	v_add_f32_e32 v98, 1.0, v99
	v_rcp_f32_e32 v102, v98
	v_mad_i64_i32 v[98:99], s[24:25], v100, s49, v[146:147]
	v_mul_f32_e32 v94, v94, v101
	v_mul_f32_e32 v94, v94, v86
	v_mul_f32_e32 v86, v90, v102
	v_mul_f32_e32 v90, 0xbfb8aa3b, v95
	v_exp_f32_e32 v90, v90
	v_mul_f32_e32 v100, 0xbfb8aa3b, v91
	v_mul_f32_e32 v101, v86, v82
	v_exp_f32_e32 v100, v100
	v_add_f32_e32 v82, 1.0, v90
	v_rcp_f32_e32 v82, v82
	v_mul_f32_e32 v90, 0xbfb8aa3b, v96
	v_exp_f32_e32 v90, v90
	v_add_f32_e32 v86, 1.0, v100
	v_mul_f32_e32 v82, v95, v82
	v_rcp_f32_e32 v86, v86
	v_mul_f32_e32 v82, v82, v87
	v_add_f32_e32 v87, 1.0, v90
	v_rcp_f32_e32 v87, v87
	v_mul_f32_e32 v86, v91, v86
	v_mul_f32_e32 v90, 0xbfb8aa3b, v92
	v_mul_f32_e32 v91, v86, v83
	v_mul_f32_e32 v83, v96, v87
	v_exp_f32_e32 v90, v90
	v_mul_f32_e32 v83, v83, v88
	v_mul_f32_e32 v87, 0xbfb8aa3b, v97
	v_mul_f32_e32 v88, 0xbfb8aa3b, v93
	v_exp_f32_e32 v87, v87
	v_exp_f32_e32 v88, v88
	v_add_f32_e32 v86, 1.0, v90
	v_rcp_f32_e32 v86, v86
	v_add_f32_e32 v87, 1.0, v87
	v_add_f32_e32 v88, 1.0, v88
	v_rcp_f32_e32 v87, v87
	v_rcp_f32_e32 v88, v88
	v_mul_f32_e32 v86, v92, v86
	v_mul_f32_e32 v90, v86, v84
	v_mul_f32_e32 v84, v97, v87
	v_mul_f32_e32 v86, v93, v88
	v_mul_f32_e32 v84, v84, v89
	v_mul_f32_e32 v85, v86, v85
	v_lshl_add_u64 v[86:87], v[98:99], 0, v[114:115]
	v_cvt_pk_bf16_f32 v82, v94, v82
	v_cvt_pk_bf16_f32 v83, v83, v84
	v_cvt_pk_bf16_f32 v84, v101, v91
	v_cvt_pk_bf16_f32 v85, v90, v85
	v_mov_b32_e32 v228, v82
	v_mov_b32_e32 v229, v83
	v_mov_b32_e32 v230, v84
	v_mov_b32_e32 v231, v85
	s_nop 1
	v_mul_f32_e32 v82, 0xbfb8aa3b, v78
	v_exp_f32_e32 v82, v82
	v_mul_f32_e32 v83, 0xbfb8aa3b, v74
	v_exp_f32_e32 v83, v83
	v_or_b32_e32 v84, 48, v154
	v_add_f32_e32 v82, 1.0, v82
	v_rcp_f32_e32 v85, v82
	v_add_f32_e32 v82, 1.0, v83
	v_rcp_f32_e32 v86, v82
	v_mad_i64_i32 v[82:83], s[24:25], v84, s49, v[146:147]
	v_mul_f32_e32 v78, v78, v85
	v_mul_f32_e32 v78, v78, v70
	v_mul_f32_e32 v70, v74, v86
	v_mul_f32_e32 v74, 0xbfb8aa3b, v79
	v_exp_f32_e32 v74, v74
	v_mul_f32_e32 v84, 0xbfb8aa3b, v75
	v_mul_f32_e32 v85, v70, v66
	v_exp_f32_e32 v84, v84
	v_add_f32_e32 v66, 1.0, v74
	v_rcp_f32_e32 v66, v66
	v_mul_f32_e32 v74, 0xbfb8aa3b, v80
	v_exp_f32_e32 v74, v74
	v_add_f32_e32 v70, 1.0, v84
	v_mul_f32_e32 v66, v79, v66
	v_rcp_f32_e32 v70, v70
	v_mul_f32_e32 v66, v66, v71
	v_add_f32_e32 v71, 1.0, v74
	v_rcp_f32_e32 v71, v71
	v_mul_f32_e32 v70, v75, v70
	v_mul_f32_e32 v74, 0xbfb8aa3b, v76
	v_mul_f32_e32 v75, v70, v67
	v_mul_f32_e32 v67, v80, v71
	v_exp_f32_e32 v74, v74
	v_mul_f32_e32 v67, v67, v72
	v_mul_f32_e32 v71, 0xbfb8aa3b, v81
	v_mul_f32_e32 v72, 0xbfb8aa3b, v77
	v_exp_f32_e32 v71, v71
	v_exp_f32_e32 v72, v72
	v_add_f32_e32 v70, 1.0, v74
	v_rcp_f32_e32 v70, v70
	v_add_f32_e32 v71, 1.0, v71
	v_add_f32_e32 v72, 1.0, v72
	v_rcp_f32_e32 v71, v71
	v_rcp_f32_e32 v72, v72
	v_mul_f32_e32 v70, v76, v70
	v_mul_f32_e32 v74, v70, v68
	v_mul_f32_e32 v68, v81, v71
	v_mul_f32_e32 v70, v77, v72
	v_mul_f32_e32 v68, v68, v73
	v_mul_f32_e32 v69, v70, v69
	v_lshl_add_u64 v[70:71], v[82:83], 0, v[114:115]
; __device__ __forceinline__ unsigned cvt_pk_bf16(float lo, float hi) { unsigned r; asm volatile("v_cvt_pk_bf16_f32 %0, %1, %2" : "=v"(r) : "v"(lo), "v"(hi)); return r; }
; DI float silu_(float x) { return x * sigmoid_(x); }
;     DI void operator()(const f32x4 (&acc)[2][2][4][2], const Unit& u, int wr, int wc, int fr, int fq) const {
;     ...
;         for (int ai = 0; ai < 2; ++ai)
; #pragma unroll
;             for (int m = 0; m < 4; ++m) { bf16_t* rowp = O + (size_t)(row0 + ai * 128 + m * 16) * ldc + col0;
;                 f32x4 v0, v1;
; #pragma unroll
;                 for (int j = 0; j < 4; ++j) { v0[j] = silu_(acc[ai][0][m][0][j]) * acc[ai][1][m][0][j]; v1[j] = silu_(acc[ai][0][m][1][j]) * acc[ai][1][m][1][j]; }
;                 u32x4 w; w.x = pg8::cvt_pk_bf16(v0[0], v0[1]); w.y = pg8::cvt_pk_bf16(v0[2], v0[3]); w.z = pg8::cvt_pk_bf16(v1[0], v1[1]); w.w = pg8::cvt_pk_bf16(v1[2], v1[3]);
;                 *(u32x4*)rowp = w; }
	v_cvt_pk_bf16_f32 v66, v78, v66
	v_cvt_pk_bf16_f32 v67, v67, v68
	v_cvt_pk_bf16_f32 v68, v85, v75
	v_cvt_pk_bf16_f32 v69, v74, v69
	v_mov_b32_e32 v232, v66
	v_mov_b32_e32 v233, v67
	v_mov_b32_e32 v234, v68
	v_mov_b32_e32 v235, v69
	s_nop 1
	v_mul_f32_e32 v66, 0xbfb8aa3b, v62
	v_exp_f32_e32 v66, v66
	v_mul_f32_e32 v67, 0xbfb8aa3b, v58
	v_exp_f32_e32 v67, v67
	v_add_u32_e32 v68, 0x80, v154
	v_add_f32_e32 v66, 1.0, v66
	v_rcp_f32_e32 v69, v66
	v_add_f32_e32 v66, 1.0, v67
	v_rcp_f32_e32 v70, v66
	v_mad_i64_i32 v[66:67], s[24:25], v68, s49, v[146:147]
	v_mul_f32_e32 v62, v62, v69
	v_mul_f32_e32 v62, v62, v54
	v_mul_f32_e32 v54, v58, v70
	v_mul_f32_e32 v58, 0xbfb8aa3b, v63
	v_exp_f32_e32 v58, v58
	v_mul_f32_e32 v68, 0xbfb8aa3b, v59
	v_mul_f32_e32 v69, v54, v50
	v_exp_f32_e32 v68, v68
	v_add_f32_e32 v50, 1.0, v58
	v_rcp_f32_e32 v50, v50
	v_mul_f32_e32 v58, 0xbfb8aa3b, v64
	v_exp_f32_e32 v58, v58
	v_add_f32_e32 v54, 1.0, v68
	v_mul_f32_e32 v50, v63, v50
	v_rcp_f32_e32 v54, v54
	v_mul_f32_e32 v50, v50, v55
	v_add_f32_e32 v55, 1.0, v58
	v_rcp_f32_e32 v55, v55
	v_mul_f32_e32 v54, v59, v54
	v_mul_f32_e32 v58, 0xbfb8aa3b, v60
	v_mul_f32_e32 v59, v54, v51
	v_mul_f32_e32 v51, v64, v55
	v_exp_f32_e32 v58, v58
	v_mul_f32_e32 v51, v51, v56
	v_mul_f32_e32 v55, 0xbfb8aa3b, v65
	v_mul_f32_e32 v56, 0xbfb8aa3b, v61
	v_exp_f32_e32 v55, v55
	v_exp_f32_e32 v56, v56
	v_add_f32_e32 v54, 1.0, v58
	v_rcp_f32_e32 v54, v54
	v_add_f32_e32 v55, 1.0, v55
	v_add_f32_e32 v56, 1.0, v56
	v_rcp_f32_e32 v55, v55
	v_rcp_f32_e32 v56, v56
	v_mul_f32_e32 v54, v60, v54
	v_mul_f32_e32 v58, v54, v52
	v_mul_f32_e32 v52, v65, v55
	v_mul_f32_e32 v54, v61, v56
	v_mul_f32_e32 v52, v52, v57
	v_mul_f32_e32 v53, v54, v53
	v_lshl_add_u64 v[54:55], v[66:67], 0, v[114:115]
	v_cvt_pk_bf16_f32 v50, v62, v50
	v_cvt_pk_bf16_f32 v51, v51, v52
	v_cvt_pk_bf16_f32 v52, v69, v59
	v_cvt_pk_bf16_f32 v53, v58, v53
	v_mov_b32_e32 v236, v50
	v_mov_b32_e32 v237, v51
	v_mov_b32_e32 v238, v52
	v_mov_b32_e32 v239, v53
	s_nop 1
	v_mul_f32_e32 v50, 0xbfb8aa3b, v46
	v_exp_f32_e32 v50, v50
	v_mul_f32_e32 v51, 0xbfb8aa3b, v42
	v_exp_f32_e32 v51, v51
	v_add_u32_e32 v52, 0x90, v154
	v_add_f32_e32 v50, 1.0, v50
	v_rcp_f32_e32 v53, v50
	v_add_f32_e32 v50, 1.0, v51
	v_rcp_f32_e32 v54, v50
	v_mad_i64_i32 v[50:51], s[24:25], v52, s49, v[146:147]
	v_mul_f32_e32 v46, v46, v53
	v_mul_f32_e32 v46, v46, v38
	v_mul_f32_e32 v38, v42, v54
	v_mul_f32_e32 v42, 0xbfb8aa3b, v47
	v_exp_f32_e32 v42, v42
	v_mul_f32_e32 v52, 0xbfb8aa3b, v43
	v_mul_f32_e32 v53, v38, v34
	v_exp_f32_e32 v52, v52
	v_add_f32_e32 v34, 1.0, v42
	v_rcp_f32_e32 v34, v34
	v_mul_f32_e32 v42, 0xbfb8aa3b, v48
	v_exp_f32_e32 v42, v42
	v_add_f32_e32 v38, 1.0, v52
	v_mul_f32_e32 v34, v47, v34
	v_rcp_f32_e32 v38, v38
	v_mul_f32_e32 v34, v34, v39
	v_add_f32_e32 v39, 1.0, v42
	v_rcp_f32_e32 v39, v39
	v_mul_f32_e32 v38, v43, v38
	v_mul_f32_e32 v42, 0xbfb8aa3b, v44
	v_mul_f32_e32 v43, v38, v35
	v_mul_f32_e32 v35, v48, v39
	v_exp_f32_e32 v42, v42
	v_mul_f32_e32 v35, v35, v40
	v_mul_f32_e32 v39, 0xbfb8aa3b, v49
	v_mul_f32_e32 v40, 0xbfb8aa3b, v45
	v_exp_f32_e32 v39, v39
	v_exp_f32_e32 v40, v40
	v_add_f32_e32 v38, 1.0, v42
	v_rcp_f32_e32 v38, v38
	v_add_f32_e32 v39, 1.0, v39
	v_add_f32_e32 v40, 1.0, v40
	v_rcp_f32_e32 v39, v39
	v_rcp_f32_e32 v40, v40
	v_mul_f32_e32 v38, v44, v38
	v_mul_f32_e32 v42, v38, v36
	v_mul_f32_e32 v36, v49, v39
	v_mul_f32_e32 v38, v45, v40
	v_mul_f32_e32 v36, v36, v41
	v_mul_f32_e32 v37, v38, v37
	v_lshl_add_u64 v[38:39], v[50:51], 0, v[114:115]
	v_cvt_pk_bf16_f32 v34, v46, v34
	v_cvt_pk_bf16_f32 v35, v35, v36
	v_cvt_pk_bf16_f32 v36, v53, v43
	v_cvt_pk_bf16_f32 v37, v42, v37
	v_mov_b32_e32 v240, v34
	v_mov_b32_e32 v241, v35
	v_mov_b32_e32 v242, v36
	v_mov_b32_e32 v243, v37
	s_nop 1
	v_mul_f32_e32 v34, 0xbfb8aa3b, v30
	v_exp_f32_e32 v34, v34
	v_mul_f32_e32 v35, 0xbfb8aa3b, v26
	v_exp_f32_e32 v35, v35
	v_add_u32_e32 v36, 0xa0, v154
	v_add_f32_e32 v34, 1.0, v34
	v_rcp_f32_e32 v37, v34
	v_add_f32_e32 v34, 1.0, v35
	v_rcp_f32_e32 v38, v34
; __device__ __forceinline__ unsigned cvt_pk_bf16(float lo, float hi) { unsigned r; asm volatile("v_cvt_pk_bf16_f32 %0, %1, %2" : "=v"(r) : "v"(lo), "v"(hi)); return r; }
; #define PG8_WAIT_V(n) asm volatile("s_waitcnt vmcnt(" #n ")" ::: "memory")
; #define PG8_BAR __builtin_amdgcn_s_barrier()
; DI float silu_(float x) { return x * sigmoid_(x); }
; template <class Epi, class Sched>
; __device__ __forceinline__ void gemm_phase(PG8_LAS unsigned char* lds, const Gemm g, const Sched& S, const Epi& E) {
;     ...
;         if (!has_next) break;
; #pragma unroll
;         for (int a = 0; a < 2; ++a)
; #pragma unroll
;             for (int b = 0; b < 2; ++b)
; #pragma unroll
;                 for (int m = 0; m < 4; ++m)
; #pragma unroll
;                     for (int n = 0; n < 2; ++n) acc[a][b][m][n] = (f32x4){0.f, 0.f, 0.f, 0.f};
;         cur = nxt; cA = nA; cB = nB; ++ui;
;     }
;     PG8_WAIT_V(0);
;     if (wr == 0) PG8_BAR;
;     PG8_BAR;
;     DI void operator()(const f32x4 (&acc)[2][2][4][2], const Unit& u, int wr, int wc, int fr, int fq) const {
;     ...
;         for (int ai = 0; ai < 2; ++ai)
; #pragma unroll
;             for (int m = 0; m < 4; ++m) { bf16_t* rowp = O + (size_t)(row0 + ai * 128 + m * 16) * ldc + col0;
;                 f32x4 v0, v1;
; #pragma unroll
;                 for (int j = 0; j < 4; ++j) { v0[j] = silu_(acc[ai][0][m][0][j]) * acc[ai][1][m][0][j]; v1[j] = silu_(acc[ai][0][m][1][j]) * acc[ai][1][m][1][j]; }
;                 u32x4 w; w.x = pg8::cvt_pk_bf16(v0[0], v0[1]); w.y = pg8::cvt_pk_bf16(v0[2], v0[3]); w.z = pg8::cvt_pk_bf16(v1[0], v1[1]); w.w = pg8::cvt_pk_bf16(v1[2], v1[3]);
;                 *(u32x4*)rowp = w; }
	v_mad_i64_i32 v[34:35], s[24:25], v36, s49, v[146:147]
	v_mul_f32_e32 v30, v30, v37
	v_mul_f32_e32 v30, v30, v22
	v_mul_f32_e32 v22, v26, v38
	v_mul_f32_e32 v26, 0xbfb8aa3b, v31
	v_exp_f32_e32 v26, v26
	v_mul_f32_e32 v36, 0xbfb8aa3b, v27
	v_mul_f32_e32 v37, v22, v18
	v_exp_f32_e32 v36, v36
	v_add_f32_e32 v18, 1.0, v26
	v_rcp_f32_e32 v18, v18
	v_mul_f32_e32 v26, 0xbfb8aa3b, v32
	v_exp_f32_e32 v26, v26
	v_add_f32_e32 v22, 1.0, v36
	v_mul_f32_e32 v18, v31, v18
	v_rcp_f32_e32 v22, v22
	v_mul_f32_e32 v18, v18, v23
	v_add_f32_e32 v23, 1.0, v26
	v_rcp_f32_e32 v23, v23
	v_mul_f32_e32 v22, v27, v22
	v_mul_f32_e32 v26, 0xbfb8aa3b, v28
	v_mul_f32_e32 v27, v22, v19
	v_mul_f32_e32 v19, v32, v23
	v_exp_f32_e32 v26, v26
	v_mul_f32_e32 v19, v19, v24
	v_mul_f32_e32 v23, 0xbfb8aa3b, v33
	v_mul_f32_e32 v24, 0xbfb8aa3b, v29
	v_exp_f32_e32 v23, v23
	v_exp_f32_e32 v24, v24
	v_add_f32_e32 v22, 1.0, v26
	v_rcp_f32_e32 v22, v22
	v_add_f32_e32 v23, 1.0, v23
	v_add_f32_e32 v24, 1.0, v24
	v_rcp_f32_e32 v23, v23
	v_rcp_f32_e32 v24, v24
	v_mul_f32_e32 v22, v28, v22
	v_mul_f32_e32 v26, v22, v20
	v_mul_f32_e32 v20, v33, v23
	v_mul_f32_e32 v22, v29, v24
	v_mul_f32_e32 v20, v20, v25
	v_mul_f32_e32 v21, v22, v21
	v_lshl_add_u64 v[22:23], v[34:35], 0, v[114:115]
	v_cvt_pk_bf16_f32 v18, v30, v18
	v_cvt_pk_bf16_f32 v19, v19, v20
	v_cvt_pk_bf16_f32 v20, v37, v27
	v_cvt_pk_bf16_f32 v21, v26, v21
	v_mov_b32_e32 v244, v18
	v_mov_b32_e32 v245, v19
	v_mov_b32_e32 v246, v20
	v_mov_b32_e32 v247, v21
	s_nop 1
	v_mul_f32_e32 v18, 0xbfb8aa3b, v14
	v_exp_f32_e32 v18, v18
	v_mul_f32_e32 v19, 0xbfb8aa3b, v10
	v_exp_f32_e32 v19, v19
	v_add_u32_e32 v20, 0xb0, v154
	v_add_f32_e32 v18, 1.0, v18
	v_rcp_f32_e32 v21, v18
	v_add_f32_e32 v18, 1.0, v19
	v_rcp_f32_e32 v22, v18
	v_mad_i64_i32 v[18:19], s[24:25], v20, s49, v[146:147]
	v_mul_f32_e32 v14, v14, v21
	v_mul_f32_e32 v14, v14, v6
	v_mul_f32_e32 v6, v10, v22
	v_mul_f32_e32 v10, 0xbfb8aa3b, v15
	v_exp_f32_e32 v10, v10
	v_mul_f32_e32 v20, 0xbfb8aa3b, v11
	v_mul_f32_e32 v21, v6, v2
	v_exp_f32_e32 v20, v20
	v_add_f32_e32 v2, 1.0, v10
	v_rcp_f32_e32 v2, v2
	v_mul_f32_e32 v10, 0xbfb8aa3b, v16
	v_exp_f32_e32 v10, v10
	v_add_f32_e32 v6, 1.0, v20
	v_mul_f32_e32 v2, v15, v2
	v_rcp_f32_e32 v6, v6
	v_mul_f32_e32 v2, v2, v7
	v_add_f32_e32 v7, 1.0, v10
	v_rcp_f32_e32 v7, v7
	v_mul_f32_e32 v6, v11, v6
	v_mul_f32_e32 v10, 0xbfb8aa3b, v12
	v_mul_f32_e32 v11, v6, v3
	v_mul_f32_e32 v3, v16, v7
	v_exp_f32_e32 v10, v10
	v_mul_f32_e32 v3, v3, v8
	v_mul_f32_e32 v7, 0xbfb8aa3b, v17
	v_mul_f32_e32 v8, 0xbfb8aa3b, v13
	v_exp_f32_e32 v7, v7
	v_exp_f32_e32 v8, v8
	v_add_f32_e32 v6, 1.0, v10
	v_rcp_f32_e32 v6, v6
	v_add_f32_e32 v7, 1.0, v7
	v_add_f32_e32 v8, 1.0, v8
	v_rcp_f32_e32 v7, v7
	v_rcp_f32_e32 v8, v8
	v_mul_f32_e32 v6, v12, v6
	v_mul_f32_e32 v10, v6, v4
	v_mul_f32_e32 v4, v17, v7
	v_mul_f32_e32 v6, v13, v8
	v_mul_f32_e32 v4, v4, v9
	v_mul_f32_e32 v5, v6, v5
	v_lshl_add_u64 v[6:7], v[18:19], 0, v[114:115]
	s_mov_b64 s[24:25], s[18:19]
	v_cvt_pk_bf16_f32 v2, v14, v2
	v_cvt_pk_bf16_f32 v3, v3, v4
	v_cvt_pk_bf16_f32 v4, v21, v11
	v_cvt_pk_bf16_f32 v5, v10, v5
	v_mov_b32_e32 v248, v2
	v_mov_b32_e32 v249, v3
	v_mov_b32_e32 v250, v4
	v_mov_b32_e32 v251, v5
	s_cbranch_vccz .LBB0_479
	s_add_u32 s100, s98, 0x2c000
	s_addc_u32 s101, s99, 0
	global_store_dwordx4 v252, v[224:227], s[100:101]
	s_add_u32 s100, s98, 0x58000
	s_addc_u32 s101, s99, 0
	global_store_dwordx4 v252, v[228:231], s[100:101]
	s_add_u32 s100, s98, 0x84000
	s_addc_u32 s101, s99, 0
	global_store_dwordx4 v252, v[232:235], s[100:101]
	s_add_u32 s100, s98, 0x160000
	s_addc_u32 s101, s99, 0
	global_store_dwordx4 v252, v[236:239], s[100:101]
	s_add_u32 s100, s98, 0x18c000
	s_addc_u32 s101, s99, 0
	global_store_dwordx4 v252, v[240:243], s[100:101]
	s_add_u32 s100, s98, 0x1b8000
	s_addc_u32 s101, s99, 0
	global_store_dwordx4 v252, v[244:247], s[100:101]
	s_add_u32 s100, s98, 0x1e4000
	s_addc_u32 s101, s99, 0
	global_store_dwordx4 v252, v[248:251], s[100:101]
	s_waitcnt vmcnt(0)
	s_cmpk_gt_u32 s3, 0xff
	s_cbranch_scc1 .LBB0_486
	s_barrier

; #define PG8_STAGE(bufoff, gbase, voff) do { _Pragma("unroll") for (int _i = 0; _i < 2; ++_i) \
;         __builtin_amdgcn_global_load_lds((const unsigned*)((const char*)(gbase) + (voff)[_i]), (PG8_LAS unsigned*)(lds + (bufoff) + ldsw + _i * 8192), 16, 0, 0); } while (0)
; #define PG8_WAIT_V(n) asm volatile("s_waitcnt vmcnt(" #n ")" ::: "memory")
; template <class Epi, class Sched>
; __device__ __forceinline__ void gemm_phase(PG8_LAS unsigned char* lds, const Gemm g, const Sched& S, const Epi& E) {
;     const int tid = threadIdx.x, wid = __builtin_amdgcn_readfirstlane(tid >> 6), lane = tid & 63, wr = wid >> 2, wc = wid & 3, fr = lane & 15, fq = lane >> 4;
;     const int K = g.K, nt = K / BK;
;     unsigned voffA[2], voffB[2];
; #pragma unroll
;     for (int i = 0; i < 2; ++i) { int R, C; stage_rc(tid * 16 + i * 8192, R, C); const int Rb = Epi::PERM ? ((R & ~31) + perm32(R & 31)) : R;
;         voffA[i] = (unsigned)(R * g.lda + C) * 2u; voffB[i] = (unsigned)(Rb * K + C) * 2u; }
;     const size_t kstep = (size_t)(BK * 2);
;     const size_t hstepA = (size_t)HALF * g.lda * 2, hstepB = (size_t)HALF * K * 2;
;     const size_t tstepA = 2 * hstepA, tstepB = 2 * hstepB;
;     const unsigned ldsw = (unsigned)wid * 1024u;
;     const int aoff = lds_byte(wr * 64 + fr, fq * 8), boff = lds_byte(wc * 32 + fr, fq * 8);
;     ...
;     Unit cur, nxt; int ui = 0;
;     if (!S.next(0, cur)) return;
;     f32x4 acc[2][2][4][2];
; #pragma unroll
;     for (int a = 0; a < 2; ++a)
; #pragma unroll
;         for (int b = 0; b < 2; ++b)
; #pragma unroll
;             for (int m = 0; m < 4; ++m)
; #pragma unroll
;                 for (int n = 0; n < 2; ++n) acc[a][b][m][n] = (f32x4){0.f, 0.f, 0.f, 0.f};
;     bf16x8 At[4][2], B0[2][2], B1[2][2];
;     const char* cA = (const char*)g.A + (size_t)cur.pm * tstepA + (g.agroup ? (size_t)(cur.pn / g.agroup) * K * 2 : (size_t)0); const char* cB = (const char*)g.Bt + (size_t)cur.pn * tstepB;
;     S.a_ready(cur);
;     PG8_STAGE(PG8_SB(0, 0), cB, voffB); PG8_STAGE(PG8_SA(0, 0), cA, voffA); PG8_STAGE(PG8_SB(0, 1), cB + hstepB, voffB); PG8_STAGE(PG8_SA(0, 1), cA + hstepA, voffA);
;     if (wr == 1) PG8_BAR;
;     PG8_WAIT_V(4); PG8_BAR;
;     PG8_STAGE(PG8_SB(1, 0), cB + kstep, voffB); PG8_STAGE(PG8_SA(1, 0), cA + kstep, voffA); PG8_STAGE(PG8_SB(1, 1), cB + hstepB + kstep, voffB);
;     PG8_WAIT_V(6); PG8_BAR;
.LBB0_1171:
	s_cmp_lt_i32 s62, 17
	s_cselect_b64 s[6:7], -1, 0
	s_and_b64 s[8:9], s[6:7], s[8:9]
	s_andn2_b64 vcc, exec, s[8:9]
	s_cbranch_vccnz .LBB0_1184
	s_mov_b64 s[98:99], 0
	s_cmpk_gt_i32 s2, 0xaff
	v_mov_b32_e32 v2, v1
	s_mov_b64 s[6:7], s[0:1]
	v_readfirstlane_b32 s3, v1
	s_cbranch_scc1 .LBB0_1184
	v_lshrrev_b32_e32 v4, 1, v1
	v_and_b32_e32 v13, 24, v4
	v_lshrrev_b32_e32 v4, 5, v1
	v_and_b32_e32 v4, 4, v4
	v_bfe_u32 v5, v1, 2, 2
	v_lshlrev_b32_e32 v2, 4, v1
	v_and_b32_e32 v3, 32, v1
	v_bfe_u32 v12, v1, 2, 4
	v_or3_b32 v4, v4, v5, v13
	v_lshrrev_b32_e32 v5, 3, v1
	s_movk_i32 s10, 0x70
	v_bitop3_b32 v10, v2, v3, 48 bitop3:0x6c
	v_and_b32_e32 v11, 64, v1
	v_and_or_b32 v6, v5, s10, v12
	s_movk_i32 s10, 0x60
	v_add_u32_e32 v14, 0x2000, v2
	v_or_b32_e32 v3, v10, v11
	v_and_or_b32 v5, v5, s10, v4
	v_lshrrev_b32_e32 v2, 7, v14
	s_movk_i32 s10, 0xf0
	s_waitcnt vmcnt(0)
	v_lshl_or_b32 v132, v5, 12, v3
	v_and_or_b32 v5, v2, s10, v12
	s_load_dwordx2 s[10:11], s[6:7], 0xc8
	s_movk_i32 s6, 0xe0
	v_and_or_b32 v2, v2, s6, v4
	s_movk_i32 s38, 0x161
	v_lshl_or_b32 v136, v2, 12, v3
	s_waitcnt lgkmcnt(0)
	s_add_u32 s30, s10, 0x10dcc000
	s_addc_u32 s31, s11, 0
	s_add_u32 s34, s10, 0x910c000
	s_addc_u32 s35, s11, 0
	s_ashr_i32 s37, s2, 31
	s_lshr_b32 s6, s37, 29
	s_add_i32 s6, s2, s6
	s_lshr_b32 s12, s3, 6
	s_ashr_i32 s13, s6, 3
	s_and_b32 s6, s6, -8
	s_lshr_b32 s7, s3, 8
	s_lshl_b32 s36, s12, 10
	s_sub_i32 s6, s2, s6
	s_cmp_lt_i32 s6, 0
	s_cselect_b32 s14, s38, 0x160
	s_mul_i32 s6, s6, s14
	s_add_i32 s6, s6, s13
	s_mul_hi_i32 s13, s6, 0x2e8ba2e9
	s_lshr_b32 s14, s13, 31
	s_ashr_i32 s13, s13, 5
	s_add_i32 s13, s13, s14
	s_lshl_b32 s14, s13, 2
	s_mulk_i32 s13, 0xb0
	s_sub_i32 s13, s6, s13
	s_sext_i32_i16 s6, s13
	s_bfe_u32 s6, s6, 0x2001d
	s_add_i32 s15, s13, s6
	s_sext_i32_i16 s6, s15
	s_and_b32 s15, s15, 0xfffc
	s_sub_i32 s13, s13, s15
	s_sext_i32_i16 s13, s13
	s_lshr_b32 s6, s6, 2
	s_add_i32 s22, s14, s13
	s_ashr_i32 s23, s22, 31
	s_bfe_i64 s[16:17], s[6:7], 0x100000
	s_lshl_b64 s[14:15], s[22:23], 20
	s_lshl_b64 s[16:17], s[16:17], 20
	s_add_u32 s26, s34, s16
	s_addc_u32 s27, s35, s17
	s_add_i32 s23, s36, 0
	s_add_i32 m0, s23, 0x10000
	v_lshl_or_b32 v130, v6, 12, v3
	global_load_lds_dwordx4 v132, s[26:27]
	s_add_i32 m0, s23, 0x12000
	s_add_u32 s24, s30, s14
	global_load_lds_dwordx4 v136, s[26:27]
	s_addc_u32 s25, s31, s15
	s_mov_b32 m0, s23
	s_add_i32 s39, s23, 0x2000
	v_lshl_or_b32 v134, v5, 12, v3
	global_load_lds_dwordx4 v130, s[24:25]
	s_mov_b32 m0, s39
	s_add_u32 s14, s26, 0x80000
	global_load_lds_dwordx4 v134, s[24:25]
	s_addc_u32 s15, s27, 0
	s_add_i32 m0, s23, 0x14000
	v_mov_b32_e32 v133, 0
	global_load_lds_dwordx4 v132, s[14:15]
	s_add_i32 m0, s23, 0x16000
	v_mov_b32_e32 v137, v133
	global_load_lds_dwordx4 v136, s[14:15]
	s_add_u32 s14, s24, 0x80000
	s_addc_u32 s15, s25, 0
	s_add_i32 s40, s23, 0x4000
	s_mov_b32 m0, s40
	s_add_i32 s41, s23, 0x6000
	global_load_lds_dwordx4 v130, s[14:15]
	s_mov_b32 m0, s41
	v_mov_b32_e32 v131, v133
	global_load_lds_dwordx4 v134, s[14:15]
	v_mov_b32_e32 v135, v133
	s_mov_b32 s42, 0
	v_lshl_add_u64 v[8:9], s[26:27], 0, v[132:133]
	v_lshl_add_u64 v[6:7], s[26:27], 0, v[136:137]
	v_lshl_add_u64 v[4:5], s[24:25], 0, v[130:131]
	s_cmp_lg_u32 s7, 1
	v_lshl_add_u64 v[2:3], s[24:25], 0, v[134:135]
	s_cbranch_scc1 .LBB0_1175
	s_barrier

; __global__ void __launch_bounds__(NTHR) fwd_kernel(Args a_k) {
;     extern __shared__ __attribute__((aligned(16))) unsigned char lds[];
	.amdhsa_kernel _Z10fwd_kernel4Args
		.amdhsa_group_segment_fixed_size 0
		.amdhsa_private_segment_fixed_size 0
		.amdhsa_kernarg_size 472
		.amdhsa_user_sgpr_count 2
		.amdhsa_user_sgpr_dispatch_ptr 0
		.amdhsa_user_sgpr_queue_ptr 0
		.amdhsa_user_sgpr_kernarg_segment_ptr 1
		.amdhsa_user_sgpr_dispatch_id 0
		.amdhsa_user_sgpr_kernarg_preload_length 0
		.amdhsa_user_sgpr_kernarg_preload_offset 0
		.amdhsa_user_sgpr_private_segment_size 0
		.amdhsa_uses_dynamic_stack 0
		.amdhsa_enable_private_segment 0
		.amdhsa_system_sgpr_workgroup_id_x 1
		.amdhsa_system_sgpr_workgroup_id_y 0
		.amdhsa_system_sgpr_workgroup_id_z 0
		.amdhsa_system_sgpr_workgroup_info 0
		.amdhsa_system_vgpr_workitem_id 2
		.amdhsa_next_free_vgpr 255
		.amdhsa_next_free_sgpr 102
		.amdhsa_accum_offset 256
		.amdhsa_reserve_vcc 1
		.amdhsa_float_round_mode_32 0
		.amdhsa_float_round_mode_16_64 0
		.amdhsa_float_denorm_mode_32 3
		.amdhsa_float_denorm_mode_16_64 3
		.amdhsa_dx10_clamp 1
		.amdhsa_ieee_mode 1
		.amdhsa_fp16_overflow 0
		.amdhsa_tg_split 0
		.amdhsa_exception_fp_ieee_invalid_op 0
		.amdhsa_exception_fp_denorm_src 0
		.amdhsa_exception_fp_ieee_div_zero 0
		.amdhsa_exception_fp_ieee_overflow 0
		.amdhsa_exception_fp_ieee_underflow 0
		.amdhsa_exception_fp_ieee_inexact 0
		.amdhsa_exception_int_div_zero 0
	.end_amdhsa_kernel

; __global__ void __launch_bounds__(NTHR) fwd_kernel(Args a_k) {
;     extern __shared__ __attribute__((aligned(16))) unsigned char lds[];
amdhsa.kernels:
  - .agpr_count:     0
    .args:
      - .offset:         0
        .size:           216
        .value_kind:     by_value
      - .offset:         216
        .size:           4
        .value_kind:     hidden_block_count_x
      - .offset:         220
        .size:           4
        .value_kind:     hidden_block_count_y
      - .offset:         224
        .size:           4
        .value_kind:     hidden_block_count_z
      - .offset:         228
        .size:           2
        .value_kind:     hidden_group_size_x
      - .offset:         230
        .size:           2
        .value_kind:     hidden_group_size_y
      - .offset:         232
        .size:           2
        .value_kind:     hidden_group_size_z
      - .offset:         234
        .size:           2
        .value_kind:     hidden_remainder_x
      - .offset:         236
        .size:           2
        .value_kind:     hidden_remainder_y
      - .offset:         238
        .size:           2
        .value_kind:     hidden_remainder_z
      - .offset:         256
        .size:           8
        .value_kind:     hidden_global_offset_x
      - .offset:         264
        .size:           8
        .value_kind:     hidden_global_offset_y
      - .offset:         272
        .size:           8
        .value_kind:     hidden_global_offset_z
      - .offset:         280
        .size:           2
        .value_kind:     hidden_grid_dims
      - .offset:         304
        .size:           8
        .value_kind:     hidden_multigrid_sync_arg
      - .offset:         336
        .size:           4
        .value_kind:     hidden_dynamic_lds_size
    .group_segment_fixed_size: 0
    .kernarg_segment_align: 8
    .kernarg_segment_size: 472
    .language:       OpenCL C
    .language_version:
      - 2
      - 0
    .max_flat_workgroup_size: 512
    .name:           _Z10fwd_kernel4Args
    .private_segment_fixed_size: 0
    .sgpr_count:     108
    .sgpr_spill_count: 8
    .symbol:         _Z10fwd_kernel4Args.kd
    .uniform_work_group_size: 1
    .uses_dynamic_stack: false
    .vgpr_count:     255
    .vgpr_spill_count: 0
    .wavefront_size: 64
